# in-proj epilogue class 0 (gelu): eight regions rewritten with packed f32 math, two chains in lockstep, in-place results (same op sequence per element)
# speedup vs baseline: 1.0115x; 1.0094x over previous
.LBB0_270:
	s_andn2_b64 vcc, exec, s[8:9]
	s_cbranch_vccnz .LBB0_272
	s_waitcnt vmcnt(0)
	s_mov_b32 s100, 0x3d372713
	s_mov_b32 s101, 0x3f4c422a
	v_mov_b32_e32 v0, 0xc038aa3b
	v_pk_mul_f32 v[148:149], v[162:163], s[100:101] op_sel_hi:[1,0]
	v_pk_mul_f32 v[150:151], v[164:165], s[100:101] op_sel_hi:[1,0]
	v_pk_mul_f32 v[148:149], v[162:163], v[148:149]
	v_pk_mul_f32 v[150:151], v[164:165], v[150:151]
	v_pk_fma_f32 v[148:149], v[162:163], v[148:149], v[162:163]
	v_pk_fma_f32 v[150:151], v[164:165], v[150:151], v[164:165]
	v_pk_mul_f32 v[148:149], v[148:149], s[100:101] op_sel:[0,1] op_sel_hi:[1,1]
	v_pk_mul_f32 v[150:151], v[150:151], s[100:101] op_sel:[0,1] op_sel_hi:[1,1]
	v_pk_mul_f32 v[148:149], v[148:149], v[0:1] op_sel_hi:[1,0]
	v_pk_mul_f32 v[150:151], v[150:151], v[0:1] op_sel_hi:[1,0]
	v_exp_f32_e32 v148, v148
	v_exp_f32_e32 v149, v149
	v_exp_f32_e32 v150, v150
	v_exp_f32_e32 v151, v151
	v_pk_add_f32 v[148:149], v[148:149], 1.0 op_sel_hi:[1,0]
	v_pk_add_f32 v[150:151], v[150:151], 1.0 op_sel_hi:[1,0]
	v_rcp_f32_e32 v148, v148
	v_rcp_f32_e32 v149, v149
	v_rcp_f32_e32 v150, v150
	v_rcp_f32_e32 v151, v151
	v_pk_mul_f32 v[162:163], v[162:163], v[148:149]
	v_pk_mul_f32 v[164:165], v[164:165], v[150:151]
	v_pk_mul_f32 v[148:149], v[142:143], s[100:101] op_sel_hi:[1,0]
	v_pk_mul_f32 v[150:151], v[144:145], s[100:101] op_sel_hi:[1,0]
	v_pk_mul_f32 v[148:149], v[142:143], v[148:149]
	v_pk_mul_f32 v[150:151], v[144:145], v[150:151]
	v_pk_fma_f32 v[148:149], v[142:143], v[148:149], v[142:143]
	v_pk_fma_f32 v[150:151], v[144:145], v[150:151], v[144:145]
	v_pk_mul_f32 v[148:149], v[148:149], s[100:101] op_sel:[0,1] op_sel_hi:[1,1]
	v_pk_mul_f32 v[150:151], v[150:151], s[100:101] op_sel:[0,1] op_sel_hi:[1,1]
	v_pk_mul_f32 v[148:149], v[148:149], v[0:1] op_sel_hi:[1,0]
	v_pk_mul_f32 v[150:151], v[150:151], v[0:1] op_sel_hi:[1,0]
	v_exp_f32_e32 v148, v148
	v_exp_f32_e32 v149, v149
	v_exp_f32_e32 v150, v150
	v_exp_f32_e32 v151, v151
	v_pk_add_f32 v[148:149], v[148:149], 1.0 op_sel_hi:[1,0]
	v_pk_add_f32 v[150:151], v[150:151], 1.0 op_sel_hi:[1,0]
	v_rcp_f32_e32 v148, v148
	v_rcp_f32_e32 v149, v149
	v_rcp_f32_e32 v150, v150
	v_rcp_f32_e32 v151, v151
	v_pk_mul_f32 v[142:143], v[142:143], v[148:149]
	v_pk_mul_f32 v[144:145], v[144:145], v[150:151]
	v_cvt_pk_bf16_f32 v145, v144, v145
	v_cvt_pk_bf16_f32 v144, v142, v143
	v_cvt_pk_bf16_f32 v142, v162, v163
	v_cvt_pk_bf16_f32 v143, v164, v165
	v_ashrrev_i32_e32 v205, 31, v204
	v_lshlrev_b64 v[146:147], 9, v[204:205]
	v_lshl_add_u64 v[146:147], v[198:199], 0, v[146:147]
	global_store_dwordx4 v[146:147], v[142:145], off
	v_pk_mul_f32 v[148:149], v[138:139], s[100:101] op_sel_hi:[1,0]
	v_pk_mul_f32 v[150:151], v[140:141], s[100:101] op_sel_hi:[1,0]
	v_pk_mul_f32 v[148:149], v[138:139], v[148:149]
	v_pk_mul_f32 v[150:151], v[140:141], v[150:151]
	v_pk_fma_f32 v[148:149], v[138:139], v[148:149], v[138:139]
	v_pk_fma_f32 v[150:151], v[140:141], v[150:151], v[140:141]
	v_pk_mul_f32 v[148:149], v[148:149], s[100:101] op_sel:[0,1] op_sel_hi:[1,1]
	v_pk_mul_f32 v[150:151], v[150:151], s[100:101] op_sel:[0,1] op_sel_hi:[1,1]
	v_pk_mul_f32 v[148:149], v[148:149], v[0:1] op_sel_hi:[1,0]
	v_pk_mul_f32 v[150:151], v[150:151], v[0:1] op_sel_hi:[1,0]
	v_exp_f32_e32 v148, v148
	v_exp_f32_e32 v149, v149
	v_exp_f32_e32 v150, v150
	v_exp_f32_e32 v151, v151
	v_pk_add_f32 v[148:149], v[148:149], 1.0 op_sel_hi:[1,0]
	v_pk_add_f32 v[150:151], v[150:151], 1.0 op_sel_hi:[1,0]
	v_rcp_f32_e32 v148, v148
	v_rcp_f32_e32 v149, v149
	v_rcp_f32_e32 v150, v150
	v_rcp_f32_e32 v151, v151
	v_pk_mul_f32 v[138:139], v[138:139], v[148:149]
	v_pk_mul_f32 v[140:141], v[140:141], v[150:151]
	v_pk_mul_f32 v[148:149], v[134:135], s[100:101] op_sel_hi:[1,0]
	v_pk_mul_f32 v[150:151], v[136:137], s[100:101] op_sel_hi:[1,0]
	v_pk_mul_f32 v[148:149], v[134:135], v[148:149]
	v_pk_mul_f32 v[150:151], v[136:137], v[150:151]
	v_pk_fma_f32 v[148:149], v[134:135], v[148:149], v[134:135]
	v_pk_fma_f32 v[150:151], v[136:137], v[150:151], v[136:137]
	v_pk_mul_f32 v[148:149], v[148:149], s[100:101] op_sel:[0,1] op_sel_hi:[1,1]
	v_pk_mul_f32 v[150:151], v[150:151], s[100:101] op_sel:[0,1] op_sel_hi:[1,1]
	v_pk_mul_f32 v[148:149], v[148:149], v[0:1] op_sel_hi:[1,0]
	v_pk_mul_f32 v[150:151], v[150:151], v[0:1] op_sel_hi:[1,0]
	v_exp_f32_e32 v148, v148
	v_exp_f32_e32 v149, v149
	v_exp_f32_e32 v150, v150
	v_exp_f32_e32 v151, v151
	v_pk_add_f32 v[148:149], v[148:149], 1.0 op_sel_hi:[1,0]
	v_pk_add_f32 v[150:151], v[150:151], 1.0 op_sel_hi:[1,0]
	v_rcp_f32_e32 v148, v148
	v_rcp_f32_e32 v149, v149
	v_rcp_f32_e32 v150, v150
	v_rcp_f32_e32 v151, v151
	v_pk_mul_f32 v[134:135], v[134:135], v[148:149]
	v_pk_mul_f32 v[136:137], v[136:137], v[150:151]
	v_cvt_pk_bf16_f32 v137, v136, v137
	v_cvt_pk_bf16_f32 v136, v134, v135
	v_cvt_pk_bf16_f32 v134, v138, v139
	v_cvt_pk_bf16_f32 v135, v140, v141
	global_store_dwordx4 v[146:147], v[134:137], off offset:64

.LBB0_315:
	s_andn2_b64 vcc, exec, s[0:1]
	s_cbranch_vccnz .LBB0_317
	s_mov_b32 s100, 0x3d372713
	s_mov_b32 s101, 0x3f4c422a
	v_mov_b32_e32 v0, 0xc038aa3b
	v_pk_mul_f32 v[136:137], v[130:131], s[100:101] op_sel_hi:[1,0]
	v_pk_mul_f32 v[138:139], v[132:133], s[100:101] op_sel_hi:[1,0]
	v_pk_mul_f32 v[136:137], v[130:131], v[136:137]
	v_pk_mul_f32 v[138:139], v[132:133], v[138:139]
	v_pk_fma_f32 v[136:137], v[130:131], v[136:137], v[130:131]
	v_pk_fma_f32 v[138:139], v[132:133], v[138:139], v[132:133]
	v_pk_mul_f32 v[136:137], v[136:137], s[100:101] op_sel:[0,1] op_sel_hi:[1,1]
	v_pk_mul_f32 v[138:139], v[138:139], s[100:101] op_sel:[0,1] op_sel_hi:[1,1]
	v_pk_mul_f32 v[136:137], v[136:137], v[0:1] op_sel_hi:[1,0]
	v_pk_mul_f32 v[138:139], v[138:139], v[0:1] op_sel_hi:[1,0]
	v_exp_f32_e32 v136, v136
	v_exp_f32_e32 v137, v137
	v_exp_f32_e32 v138, v138
	v_exp_f32_e32 v139, v139
	v_pk_add_f32 v[136:137], v[136:137], 1.0 op_sel_hi:[1,0]
	v_pk_add_f32 v[138:139], v[138:139], 1.0 op_sel_hi:[1,0]
	v_rcp_f32_e32 v136, v136
	v_rcp_f32_e32 v137, v137
	v_rcp_f32_e32 v138, v138
	v_rcp_f32_e32 v139, v139
	v_pk_mul_f32 v[130:131], v[130:131], v[136:137]
	v_pk_mul_f32 v[132:133], v[132:133], v[138:139]
	v_pk_mul_f32 v[136:137], v[126:127], s[100:101] op_sel_hi:[1,0]
	v_pk_mul_f32 v[138:139], v[128:129], s[100:101] op_sel_hi:[1,0]
	v_pk_mul_f32 v[136:137], v[126:127], v[136:137]
	v_pk_mul_f32 v[138:139], v[128:129], v[138:139]
	v_pk_fma_f32 v[136:137], v[126:127], v[136:137], v[126:127]
	v_pk_fma_f32 v[138:139], v[128:129], v[138:139], v[128:129]
	v_pk_mul_f32 v[136:137], v[136:137], s[100:101] op_sel:[0,1] op_sel_hi:[1,1]
	v_pk_mul_f32 v[138:139], v[138:139], s[100:101] op_sel:[0,1] op_sel_hi:[1,1]
	v_pk_mul_f32 v[136:137], v[136:137], v[0:1] op_sel_hi:[1,0]
	v_pk_mul_f32 v[138:139], v[138:139], v[0:1] op_sel_hi:[1,0]
	v_exp_f32_e32 v136, v136
	v_exp_f32_e32 v137, v137
	v_exp_f32_e32 v138, v138
	v_exp_f32_e32 v139, v139
	v_pk_add_f32 v[136:137], v[136:137], 1.0 op_sel_hi:[1,0]
	v_pk_add_f32 v[138:139], v[138:139], 1.0 op_sel_hi:[1,0]
	v_rcp_f32_e32 v136, v136
	v_rcp_f32_e32 v137, v137
	v_rcp_f32_e32 v138, v138
	v_rcp_f32_e32 v139, v139
	v_pk_mul_f32 v[126:127], v[126:127], v[136:137]
	v_pk_mul_f32 v[128:129], v[128:129], v[138:139]
	v_cvt_pk_bf16_f32 v129, v128, v129
	v_cvt_pk_bf16_f32 v128, v126, v127
	v_cvt_pk_bf16_f32 v126, v130, v131
	v_cvt_pk_bf16_f32 v127, v132, v133
	v_ashrrev_i32_e32 v205, 31, v204
	s_waitcnt vmcnt(3)
	v_lshlrev_b64 v[134:135], 9, v[204:205]
	s_waitcnt vmcnt(1)
	v_mov_b64_e32 v[142:143], v[154:155]
	s_waitcnt vmcnt(0)
	v_mov_b64_e32 v[164:165], v[160:161]
	v_mov_b64_e32 v[144:145], v[156:157]
	v_mov_b64_e32 v[162:163], v[158:159]
	v_lshl_add_u64 v[130:131], v[198:199], 0, v[134:135]
	global_store_dwordx4 v[130:131], v[126:129], off
	v_pk_mul_f32 v[136:137], v[122:123], s[100:101] op_sel_hi:[1,0]
	v_pk_mul_f32 v[138:139], v[124:125], s[100:101] op_sel_hi:[1,0]
	v_pk_mul_f32 v[136:137], v[122:123], v[136:137]
	v_pk_mul_f32 v[138:139], v[124:125], v[138:139]
	v_pk_fma_f32 v[136:137], v[122:123], v[136:137], v[122:123]
	v_pk_fma_f32 v[138:139], v[124:125], v[138:139], v[124:125]
	v_pk_mul_f32 v[136:137], v[136:137], s[100:101] op_sel:[0,1] op_sel_hi:[1,1]
	v_pk_mul_f32 v[138:139], v[138:139], s[100:101] op_sel:[0,1] op_sel_hi:[1,1]
	v_pk_mul_f32 v[136:137], v[136:137], v[0:1] op_sel_hi:[1,0]
	v_pk_mul_f32 v[138:139], v[138:139], v[0:1] op_sel_hi:[1,0]
	v_exp_f32_e32 v136, v136
	v_exp_f32_e32 v137, v137
	v_exp_f32_e32 v138, v138
	v_exp_f32_e32 v139, v139
	v_pk_add_f32 v[136:137], v[136:137], 1.0 op_sel_hi:[1,0]
	v_pk_add_f32 v[138:139], v[138:139], 1.0 op_sel_hi:[1,0]
	v_rcp_f32_e32 v136, v136
	v_rcp_f32_e32 v137, v137
	v_rcp_f32_e32 v138, v138
	v_rcp_f32_e32 v139, v139
	v_pk_mul_f32 v[122:123], v[122:123], v[136:137]
	v_pk_mul_f32 v[124:125], v[124:125], v[138:139]
	v_pk_mul_f32 v[136:137], v[118:119], s[100:101] op_sel_hi:[1,0]
	v_pk_mul_f32 v[138:139], v[120:121], s[100:101] op_sel_hi:[1,0]
	v_pk_mul_f32 v[136:137], v[118:119], v[136:137]
	v_pk_mul_f32 v[138:139], v[120:121], v[138:139]
	v_pk_fma_f32 v[136:137], v[118:119], v[136:137], v[118:119]
	v_pk_fma_f32 v[138:139], v[120:121], v[138:139], v[120:121]
	v_pk_mul_f32 v[136:137], v[136:137], s[100:101] op_sel:[0,1] op_sel_hi:[1,1]
	v_pk_mul_f32 v[138:139], v[138:139], s[100:101] op_sel:[0,1] op_sel_hi:[1,1]
	v_pk_mul_f32 v[136:137], v[136:137], v[0:1] op_sel_hi:[1,0]
	v_pk_mul_f32 v[138:139], v[138:139], v[0:1] op_sel_hi:[1,0]
	v_exp_f32_e32 v136, v136
	v_exp_f32_e32 v137, v137
	v_exp_f32_e32 v138, v138
	v_exp_f32_e32 v139, v139
	v_pk_add_f32 v[136:137], v[136:137], 1.0 op_sel_hi:[1,0]
	v_pk_add_f32 v[138:139], v[138:139], 1.0 op_sel_hi:[1,0]
	v_rcp_f32_e32 v136, v136
	v_rcp_f32_e32 v137, v137
	v_rcp_f32_e32 v138, v138
	v_rcp_f32_e32 v139, v139
	v_pk_mul_f32 v[118:119], v[118:119], v[136:137]
	v_pk_mul_f32 v[120:121], v[120:121], v[138:139]
	v_cvt_pk_bf16_f32 v121, v120, v121
	v_cvt_pk_bf16_f32 v120, v118, v119
	v_cvt_pk_bf16_f32 v118, v122, v123
	v_cvt_pk_bf16_f32 v119, v124, v125
	v_mov_b64_e32 v[134:135], v[146:147]
	v_mov_b64_e32 v[138:139], v[150:151]
	v_mov_b64_e32 v[136:137], v[148:149]
	v_mov_b64_e32 v[140:141], v[152:153]
	global_store_dwordx4 v[130:131], v[118:121], off offset:64

.LBB0_360:
	s_andn2_b64 vcc, exec, s[0:1]
	s_cbranch_vccnz .LBB0_362
	s_mov_b32 s100, 0x3d372713
	s_mov_b32 s101, 0x3f4c422a
	v_mov_b32_e32 v0, 0xc038aa3b
	v_pk_mul_f32 v[120:121], v[114:115], s[100:101] op_sel_hi:[1,0]
	v_pk_mul_f32 v[122:123], v[116:117], s[100:101] op_sel_hi:[1,0]
	v_pk_mul_f32 v[120:121], v[114:115], v[120:121]
	v_pk_mul_f32 v[122:123], v[116:117], v[122:123]
	v_pk_fma_f32 v[120:121], v[114:115], v[120:121], v[114:115]
	v_pk_fma_f32 v[122:123], v[116:117], v[122:123], v[116:117]
	v_pk_mul_f32 v[120:121], v[120:121], s[100:101] op_sel:[0,1] op_sel_hi:[1,1]
	v_pk_mul_f32 v[122:123], v[122:123], s[100:101] op_sel:[0,1] op_sel_hi:[1,1]
	v_pk_mul_f32 v[120:121], v[120:121], v[0:1] op_sel_hi:[1,0]
	v_pk_mul_f32 v[122:123], v[122:123], v[0:1] op_sel_hi:[1,0]
	v_exp_f32_e32 v120, v120
	v_exp_f32_e32 v121, v121
	v_exp_f32_e32 v122, v122
	v_exp_f32_e32 v123, v123
	v_pk_add_f32 v[120:121], v[120:121], 1.0 op_sel_hi:[1,0]
	v_pk_add_f32 v[122:123], v[122:123], 1.0 op_sel_hi:[1,0]
	v_rcp_f32_e32 v120, v120
	v_rcp_f32_e32 v121, v121
	v_rcp_f32_e32 v122, v122
	v_rcp_f32_e32 v123, v123
	v_pk_mul_f32 v[114:115], v[114:115], v[120:121]
	v_pk_mul_f32 v[116:117], v[116:117], v[122:123]
	v_pk_mul_f32 v[120:121], v[110:111], s[100:101] op_sel_hi:[1,0]
	v_pk_mul_f32 v[122:123], v[112:113], s[100:101] op_sel_hi:[1,0]
	v_pk_mul_f32 v[120:121], v[110:111], v[120:121]
	v_pk_mul_f32 v[122:123], v[112:113], v[122:123]
	v_pk_fma_f32 v[120:121], v[110:111], v[120:121], v[110:111]
	v_pk_fma_f32 v[122:123], v[112:113], v[122:123], v[112:113]
	v_pk_mul_f32 v[120:121], v[120:121], s[100:101] op_sel:[0,1] op_sel_hi:[1,1]
	v_pk_mul_f32 v[122:123], v[122:123], s[100:101] op_sel:[0,1] op_sel_hi:[1,1]
	v_pk_mul_f32 v[120:121], v[120:121], v[0:1] op_sel_hi:[1,0]
	v_pk_mul_f32 v[122:123], v[122:123], v[0:1] op_sel_hi:[1,0]
	v_exp_f32_e32 v120, v120
	v_exp_f32_e32 v121, v121
	v_exp_f32_e32 v122, v122
	v_exp_f32_e32 v123, v123
	v_pk_add_f32 v[120:121], v[120:121], 1.0 op_sel_hi:[1,0]
	v_pk_add_f32 v[122:123], v[122:123], 1.0 op_sel_hi:[1,0]
	v_rcp_f32_e32 v120, v120
	v_rcp_f32_e32 v121, v121
	v_rcp_f32_e32 v122, v122
	v_rcp_f32_e32 v123, v123
	v_pk_mul_f32 v[110:111], v[110:111], v[120:121]
	v_pk_mul_f32 v[112:113], v[112:113], v[122:123]
	v_cvt_pk_bf16_f32 v113, v112, v113
	v_cvt_pk_bf16_f32 v112, v110, v111
	v_cvt_pk_bf16_f32 v110, v114, v115
	v_cvt_pk_bf16_f32 v111, v116, v117
	v_ashrrev_i32_e32 v147, 31, v146
	s_waitcnt vmcnt(3)
	v_lshlrev_b64 v[118:119], 9, v[146:147]
	s_waitcnt vmcnt(1)
	v_mov_b64_e32 v[126:127], v[142:143]
	s_waitcnt vmcnt(0)
	v_mov_b64_e32 v[130:131], v[162:163]
	v_mov_b64_e32 v[128:129], v[144:145]
	v_mov_b64_e32 v[132:133], v[164:165]
	v_lshl_add_u64 v[114:115], v[198:199], 0, v[118:119]
	global_store_dwordx4 v[114:115], v[110:113], off
	v_pk_mul_f32 v[120:121], v[106:107], s[100:101] op_sel_hi:[1,0]
	v_pk_mul_f32 v[122:123], v[108:109], s[100:101] op_sel_hi:[1,0]
	v_pk_mul_f32 v[120:121], v[106:107], v[120:121]
	v_pk_mul_f32 v[122:123], v[108:109], v[122:123]
	v_pk_fma_f32 v[120:121], v[106:107], v[120:121], v[106:107]
	v_pk_fma_f32 v[122:123], v[108:109], v[122:123], v[108:109]
	v_pk_mul_f32 v[120:121], v[120:121], s[100:101] op_sel:[0,1] op_sel_hi:[1,1]
	v_pk_mul_f32 v[122:123], v[122:123], s[100:101] op_sel:[0,1] op_sel_hi:[1,1]
	v_pk_mul_f32 v[120:121], v[120:121], v[0:1] op_sel_hi:[1,0]
	v_pk_mul_f32 v[122:123], v[122:123], v[0:1] op_sel_hi:[1,0]
	v_exp_f32_e32 v120, v120
	v_exp_f32_e32 v121, v121
	v_exp_f32_e32 v122, v122
	v_exp_f32_e32 v123, v123
	v_pk_add_f32 v[120:121], v[120:121], 1.0 op_sel_hi:[1,0]
	v_pk_add_f32 v[122:123], v[122:123], 1.0 op_sel_hi:[1,0]
	v_rcp_f32_e32 v120, v120
	v_rcp_f32_e32 v121, v121
	v_rcp_f32_e32 v122, v122
	v_rcp_f32_e32 v123, v123
	v_pk_mul_f32 v[106:107], v[106:107], v[120:121]
	v_pk_mul_f32 v[108:109], v[108:109], v[122:123]
	v_pk_mul_f32 v[120:121], v[102:103], s[100:101] op_sel_hi:[1,0]
	v_pk_mul_f32 v[122:123], v[104:105], s[100:101] op_sel_hi:[1,0]
	v_pk_mul_f32 v[120:121], v[102:103], v[120:121]
	v_pk_mul_f32 v[122:123], v[104:105], v[122:123]
	v_pk_fma_f32 v[120:121], v[102:103], v[120:121], v[102:103]
	v_pk_fma_f32 v[122:123], v[104:105], v[122:123], v[104:105]
	v_pk_mul_f32 v[120:121], v[120:121], s[100:101] op_sel:[0,1] op_sel_hi:[1,1]
	v_pk_mul_f32 v[122:123], v[122:123], s[100:101] op_sel:[0,1] op_sel_hi:[1,1]
	v_pk_mul_f32 v[120:121], v[120:121], v[0:1] op_sel_hi:[1,0]
	v_pk_mul_f32 v[122:123], v[122:123], v[0:1] op_sel_hi:[1,0]
	v_exp_f32_e32 v120, v120
	v_exp_f32_e32 v121, v121
	v_exp_f32_e32 v122, v122
	v_exp_f32_e32 v123, v123
	v_pk_add_f32 v[120:121], v[120:121], 1.0 op_sel_hi:[1,0]
	v_pk_add_f32 v[122:123], v[122:123], 1.0 op_sel_hi:[1,0]
	v_rcp_f32_e32 v120, v120
	v_rcp_f32_e32 v121, v121
	v_rcp_f32_e32 v122, v122
	v_rcp_f32_e32 v123, v123
	v_pk_mul_f32 v[102:103], v[102:103], v[120:121]
	v_pk_mul_f32 v[104:105], v[104:105], v[122:123]
	v_cvt_pk_bf16_f32 v105, v104, v105
	v_cvt_pk_bf16_f32 v104, v102, v103
	v_cvt_pk_bf16_f32 v102, v106, v107
	v_cvt_pk_bf16_f32 v103, v108, v109
	v_mov_b64_e32 v[118:119], v[134:135]
	v_mov_b64_e32 v[122:123], v[138:139]
	v_mov_b64_e32 v[120:121], v[136:137]
	v_mov_b64_e32 v[124:125], v[140:141]
	global_store_dwordx4 v[114:115], v[102:105], off offset:64

.LBB0_405:
	s_andn2_b64 vcc, exec, s[0:1]
	s_cbranch_vccnz .LBB0_407
	s_mov_b32 s100, 0x3d372713
	s_mov_b32 s101, 0x3f4c422a
	v_mov_b32_e32 v0, 0xc038aa3b
	v_pk_mul_f32 v[104:105], v[98:99], s[100:101] op_sel_hi:[1,0]
	v_pk_mul_f32 v[106:107], v[100:101], s[100:101] op_sel_hi:[1,0]
	v_pk_mul_f32 v[104:105], v[98:99], v[104:105]
	v_pk_mul_f32 v[106:107], v[100:101], v[106:107]
	v_pk_fma_f32 v[104:105], v[98:99], v[104:105], v[98:99]
	v_pk_fma_f32 v[106:107], v[100:101], v[106:107], v[100:101]
	v_pk_mul_f32 v[104:105], v[104:105], s[100:101] op_sel:[0,1] op_sel_hi:[1,1]
	v_pk_mul_f32 v[106:107], v[106:107], s[100:101] op_sel:[0,1] op_sel_hi:[1,1]
	v_pk_mul_f32 v[104:105], v[104:105], v[0:1] op_sel_hi:[1,0]
	v_pk_mul_f32 v[106:107], v[106:107], v[0:1] op_sel_hi:[1,0]
	v_exp_f32_e32 v104, v104
	v_exp_f32_e32 v105, v105
	v_exp_f32_e32 v106, v106
	v_exp_f32_e32 v107, v107
	v_pk_add_f32 v[104:105], v[104:105], 1.0 op_sel_hi:[1,0]
	v_pk_add_f32 v[106:107], v[106:107], 1.0 op_sel_hi:[1,0]
	v_rcp_f32_e32 v104, v104
	v_rcp_f32_e32 v105, v105
	v_rcp_f32_e32 v106, v106
	v_rcp_f32_e32 v107, v107
	v_pk_mul_f32 v[98:99], v[98:99], v[104:105]
	v_pk_mul_f32 v[100:101], v[100:101], v[106:107]
	v_pk_mul_f32 v[104:105], v[94:95], s[100:101] op_sel_hi:[1,0]
	v_pk_mul_f32 v[106:107], v[96:97], s[100:101] op_sel_hi:[1,0]
	v_pk_mul_f32 v[104:105], v[94:95], v[104:105]
	v_pk_mul_f32 v[106:107], v[96:97], v[106:107]
	v_pk_fma_f32 v[104:105], v[94:95], v[104:105], v[94:95]
	v_pk_fma_f32 v[106:107], v[96:97], v[106:107], v[96:97]
	v_pk_mul_f32 v[104:105], v[104:105], s[100:101] op_sel:[0,1] op_sel_hi:[1,1]
	v_pk_mul_f32 v[106:107], v[106:107], s[100:101] op_sel:[0,1] op_sel_hi:[1,1]
	v_pk_mul_f32 v[104:105], v[104:105], v[0:1] op_sel_hi:[1,0]
	v_pk_mul_f32 v[106:107], v[106:107], v[0:1] op_sel_hi:[1,0]
	v_exp_f32_e32 v104, v104
	v_exp_f32_e32 v105, v105
	v_exp_f32_e32 v106, v106
	v_exp_f32_e32 v107, v107
	v_pk_add_f32 v[104:105], v[104:105], 1.0 op_sel_hi:[1,0]
	v_pk_add_f32 v[106:107], v[106:107], 1.0 op_sel_hi:[1,0]
	v_rcp_f32_e32 v104, v104
	v_rcp_f32_e32 v105, v105
	v_rcp_f32_e32 v106, v106
	v_rcp_f32_e32 v107, v107
	v_pk_mul_f32 v[94:95], v[94:95], v[104:105]
	v_pk_mul_f32 v[96:97], v[96:97], v[106:107]
	v_cvt_pk_bf16_f32 v97, v96, v97
	v_cvt_pk_bf16_f32 v96, v94, v95
	v_cvt_pk_bf16_f32 v94, v98, v99
	v_cvt_pk_bf16_f32 v95, v100, v101
	v_ashrrev_i32_e32 v135, 31, v134
	s_waitcnt vmcnt(3)
	v_lshlrev_b64 v[102:103], 9, v[134:135]
	s_waitcnt vmcnt(1)
	v_mov_b64_e32 v[110:111], v[126:127]
	s_waitcnt vmcnt(0)
	v_mov_b64_e32 v[114:115], v[130:131]
	v_mov_b64_e32 v[112:113], v[128:129]
	v_mov_b64_e32 v[116:117], v[132:133]
	v_lshl_add_u64 v[98:99], v[198:199], 0, v[102:103]
	global_store_dwordx4 v[98:99], v[94:97], off
	v_pk_mul_f32 v[104:105], v[90:91], s[100:101] op_sel_hi:[1,0]
	v_pk_mul_f32 v[106:107], v[92:93], s[100:101] op_sel_hi:[1,0]
	v_pk_mul_f32 v[104:105], v[90:91], v[104:105]
	v_pk_mul_f32 v[106:107], v[92:93], v[106:107]
	v_pk_fma_f32 v[104:105], v[90:91], v[104:105], v[90:91]
	v_pk_fma_f32 v[106:107], v[92:93], v[106:107], v[92:93]
	v_pk_mul_f32 v[104:105], v[104:105], s[100:101] op_sel:[0,1] op_sel_hi:[1,1]
	v_pk_mul_f32 v[106:107], v[106:107], s[100:101] op_sel:[0,1] op_sel_hi:[1,1]
	v_pk_mul_f32 v[104:105], v[104:105], v[0:1] op_sel_hi:[1,0]
	v_pk_mul_f32 v[106:107], v[106:107], v[0:1] op_sel_hi:[1,0]
	v_exp_f32_e32 v104, v104
	v_exp_f32_e32 v105, v105
	v_exp_f32_e32 v106, v106
	v_exp_f32_e32 v107, v107
	v_pk_add_f32 v[104:105], v[104:105], 1.0 op_sel_hi:[1,0]
	v_pk_add_f32 v[106:107], v[106:107], 1.0 op_sel_hi:[1,0]
	v_rcp_f32_e32 v104, v104
	v_rcp_f32_e32 v105, v105
	v_rcp_f32_e32 v106, v106
	v_rcp_f32_e32 v107, v107
	v_pk_mul_f32 v[90:91], v[90:91], v[104:105]
	v_pk_mul_f32 v[92:93], v[92:93], v[106:107]
	v_pk_mul_f32 v[104:105], v[86:87], s[100:101] op_sel_hi:[1,0]
	v_pk_mul_f32 v[106:107], v[88:89], s[100:101] op_sel_hi:[1,0]
	v_pk_mul_f32 v[104:105], v[86:87], v[104:105]
	v_pk_mul_f32 v[106:107], v[88:89], v[106:107]
	v_pk_fma_f32 v[104:105], v[86:87], v[104:105], v[86:87]
	v_pk_fma_f32 v[106:107], v[88:89], v[106:107], v[88:89]
	v_pk_mul_f32 v[104:105], v[104:105], s[100:101] op_sel:[0,1] op_sel_hi:[1,1]
	v_pk_mul_f32 v[106:107], v[106:107], s[100:101] op_sel:[0,1] op_sel_hi:[1,1]
	v_pk_mul_f32 v[104:105], v[104:105], v[0:1] op_sel_hi:[1,0]
	v_pk_mul_f32 v[106:107], v[106:107], v[0:1] op_sel_hi:[1,0]
	v_exp_f32_e32 v104, v104
	v_exp_f32_e32 v105, v105
	v_exp_f32_e32 v106, v106
	v_exp_f32_e32 v107, v107
	v_pk_add_f32 v[104:105], v[104:105], 1.0 op_sel_hi:[1,0]
	v_pk_add_f32 v[106:107], v[106:107], 1.0 op_sel_hi:[1,0]
	v_rcp_f32_e32 v104, v104
	v_rcp_f32_e32 v105, v105
	v_rcp_f32_e32 v106, v106
	v_rcp_f32_e32 v107, v107
	v_pk_mul_f32 v[86:87], v[86:87], v[104:105]
	v_pk_mul_f32 v[88:89], v[88:89], v[106:107]
	v_cvt_pk_bf16_f32 v89, v88, v89
	v_cvt_pk_bf16_f32 v88, v86, v87
	v_cvt_pk_bf16_f32 v86, v90, v91
	v_cvt_pk_bf16_f32 v87, v92, v93
	v_mov_b64_e32 v[102:103], v[118:119]
	v_mov_b64_e32 v[106:107], v[122:123]
	v_mov_b64_e32 v[104:105], v[120:121]
	v_mov_b64_e32 v[108:109], v[124:125]
	global_store_dwordx4 v[98:99], v[86:89], off offset:64

.LBB0_451:
	s_andn2_b64 vcc, exec, s[0:1]
	s_cbranch_vccnz .LBB0_453
	s_mov_b32 s100, 0x3d372713
	s_mov_b32 s101, 0x3f4c422a
	v_mov_b32_e32 v0, 0xc038aa3b
	v_pk_mul_f32 v[88:89], v[82:83], s[100:101] op_sel_hi:[1,0]
	v_pk_mul_f32 v[90:91], v[84:85], s[100:101] op_sel_hi:[1,0]
	v_pk_mul_f32 v[88:89], v[82:83], v[88:89]
	v_pk_mul_f32 v[90:91], v[84:85], v[90:91]
	v_pk_fma_f32 v[88:89], v[82:83], v[88:89], v[82:83]
	v_pk_fma_f32 v[90:91], v[84:85], v[90:91], v[84:85]
	v_pk_mul_f32 v[88:89], v[88:89], s[100:101] op_sel:[0,1] op_sel_hi:[1,1]
	v_pk_mul_f32 v[90:91], v[90:91], s[100:101] op_sel:[0,1] op_sel_hi:[1,1]
	v_pk_mul_f32 v[88:89], v[88:89], v[0:1] op_sel_hi:[1,0]
	v_pk_mul_f32 v[90:91], v[90:91], v[0:1] op_sel_hi:[1,0]
	v_exp_f32_e32 v88, v88
	v_exp_f32_e32 v89, v89
	v_exp_f32_e32 v90, v90
	v_exp_f32_e32 v91, v91
	v_pk_add_f32 v[88:89], v[88:89], 1.0 op_sel_hi:[1,0]
	v_pk_add_f32 v[90:91], v[90:91], 1.0 op_sel_hi:[1,0]
	v_rcp_f32_e32 v88, v88
	v_rcp_f32_e32 v89, v89
	v_rcp_f32_e32 v90, v90
	v_rcp_f32_e32 v91, v91
	v_pk_mul_f32 v[82:83], v[82:83], v[88:89]
	v_pk_mul_f32 v[84:85], v[84:85], v[90:91]
	v_pk_mul_f32 v[88:89], v[78:79], s[100:101] op_sel_hi:[1,0]
	v_pk_mul_f32 v[90:91], v[80:81], s[100:101] op_sel_hi:[1,0]
	v_pk_mul_f32 v[88:89], v[78:79], v[88:89]
	v_pk_mul_f32 v[90:91], v[80:81], v[90:91]
	v_pk_fma_f32 v[88:89], v[78:79], v[88:89], v[78:79]
	v_pk_fma_f32 v[90:91], v[80:81], v[90:91], v[80:81]
	v_pk_mul_f32 v[88:89], v[88:89], s[100:101] op_sel:[0,1] op_sel_hi:[1,1]
	v_pk_mul_f32 v[90:91], v[90:91], s[100:101] op_sel:[0,1] op_sel_hi:[1,1]
	v_pk_mul_f32 v[88:89], v[88:89], v[0:1] op_sel_hi:[1,0]
	v_pk_mul_f32 v[90:91], v[90:91], v[0:1] op_sel_hi:[1,0]
	v_exp_f32_e32 v88, v88
	v_exp_f32_e32 v89, v89
	v_exp_f32_e32 v90, v90
	v_exp_f32_e32 v91, v91
	v_pk_add_f32 v[88:89], v[88:89], 1.0 op_sel_hi:[1,0]
	v_pk_add_f32 v[90:91], v[90:91], 1.0 op_sel_hi:[1,0]
	v_rcp_f32_e32 v88, v88
	v_rcp_f32_e32 v89, v89
	v_rcp_f32_e32 v90, v90
	v_rcp_f32_e32 v91, v91
	v_pk_mul_f32 v[78:79], v[78:79], v[88:89]
	v_pk_mul_f32 v[80:81], v[80:81], v[90:91]
	v_cvt_pk_bf16_f32 v81, v80, v81
	v_cvt_pk_bf16_f32 v80, v78, v79
	v_cvt_pk_bf16_f32 v78, v82, v83
	v_cvt_pk_bf16_f32 v79, v84, v85
	v_ashrrev_i32_e32 v119, 31, v118
	s_waitcnt vmcnt(3)
	v_lshlrev_b64 v[86:87], 9, v[118:119]
	s_waitcnt vmcnt(1)
	v_mov_b64_e32 v[94:95], v[110:111]
	s_waitcnt vmcnt(0)
	v_mov_b64_e32 v[98:99], v[114:115]
	v_mov_b64_e32 v[96:97], v[112:113]
	v_mov_b64_e32 v[100:101], v[116:117]
	v_lshl_add_u64 v[82:83], v[198:199], 0, v[86:87]
	global_store_dwordx4 v[82:83], v[78:81], off
	v_pk_mul_f32 v[88:89], v[74:75], s[100:101] op_sel_hi:[1,0]
	v_pk_mul_f32 v[90:91], v[76:77], s[100:101] op_sel_hi:[1,0]
	v_pk_mul_f32 v[88:89], v[74:75], v[88:89]
	v_pk_mul_f32 v[90:91], v[76:77], v[90:91]
	v_pk_fma_f32 v[88:89], v[74:75], v[88:89], v[74:75]
	v_pk_fma_f32 v[90:91], v[76:77], v[90:91], v[76:77]
	v_pk_mul_f32 v[88:89], v[88:89], s[100:101] op_sel:[0,1] op_sel_hi:[1,1]
	v_pk_mul_f32 v[90:91], v[90:91], s[100:101] op_sel:[0,1] op_sel_hi:[1,1]
	v_pk_mul_f32 v[88:89], v[88:89], v[0:1] op_sel_hi:[1,0]
	v_pk_mul_f32 v[90:91], v[90:91], v[0:1] op_sel_hi:[1,0]
	v_exp_f32_e32 v88, v88
	v_exp_f32_e32 v89, v89
	v_exp_f32_e32 v90, v90
	v_exp_f32_e32 v91, v91
	v_pk_add_f32 v[88:89], v[88:89], 1.0 op_sel_hi:[1,0]
	v_pk_add_f32 v[90:91], v[90:91], 1.0 op_sel_hi:[1,0]
	v_rcp_f32_e32 v88, v88
	v_rcp_f32_e32 v89, v89
	v_rcp_f32_e32 v90, v90
	v_rcp_f32_e32 v91, v91
	v_pk_mul_f32 v[74:75], v[74:75], v[88:89]
	v_pk_mul_f32 v[76:77], v[76:77], v[90:91]
	v_pk_mul_f32 v[88:89], v[70:71], s[100:101] op_sel_hi:[1,0]
	v_pk_mul_f32 v[90:91], v[72:73], s[100:101] op_sel_hi:[1,0]
	v_pk_mul_f32 v[88:89], v[70:71], v[88:89]
	v_pk_mul_f32 v[90:91], v[72:73], v[90:91]
	v_pk_fma_f32 v[88:89], v[70:71], v[88:89], v[70:71]
	v_pk_fma_f32 v[90:91], v[72:73], v[90:91], v[72:73]
	v_pk_mul_f32 v[88:89], v[88:89], s[100:101] op_sel:[0,1] op_sel_hi:[1,1]
	v_pk_mul_f32 v[90:91], v[90:91], s[100:101] op_sel:[0,1] op_sel_hi:[1,1]
	v_pk_mul_f32 v[88:89], v[88:89], v[0:1] op_sel_hi:[1,0]
	v_pk_mul_f32 v[90:91], v[90:91], v[0:1] op_sel_hi:[1,0]
	v_exp_f32_e32 v88, v88
	v_exp_f32_e32 v89, v89
	v_exp_f32_e32 v90, v90
	v_exp_f32_e32 v91, v91
	v_pk_add_f32 v[88:89], v[88:89], 1.0 op_sel_hi:[1,0]
	v_pk_add_f32 v[90:91], v[90:91], 1.0 op_sel_hi:[1,0]
	v_rcp_f32_e32 v88, v88
	v_rcp_f32_e32 v89, v89
	v_rcp_f32_e32 v90, v90
	v_rcp_f32_e32 v91, v91
	v_pk_mul_f32 v[70:71], v[70:71], v[88:89]
	v_pk_mul_f32 v[72:73], v[72:73], v[90:91]
	v_cvt_pk_bf16_f32 v73, v72, v73
	v_cvt_pk_bf16_f32 v72, v70, v71
	v_cvt_pk_bf16_f32 v70, v74, v75
	v_cvt_pk_bf16_f32 v71, v76, v77
	v_mov_b64_e32 v[86:87], v[102:103]
	v_mov_b64_e32 v[90:91], v[106:107]
	v_mov_b64_e32 v[88:89], v[104:105]
	v_mov_b64_e32 v[92:93], v[108:109]
	global_store_dwordx4 v[82:83], v[70:73], off offset:64

.LBB0_497:
	s_andn2_b64 vcc, exec, s[0:1]
	s_cbranch_vccnz .LBB0_499
	s_mov_b32 s100, 0x3d372713
	s_mov_b32 s101, 0x3f4c422a
	v_mov_b32_e32 v0, 0xc038aa3b
	v_pk_mul_f32 v[72:73], v[66:67], s[100:101] op_sel_hi:[1,0]
	v_pk_mul_f32 v[74:75], v[68:69], s[100:101] op_sel_hi:[1,0]
	v_pk_mul_f32 v[72:73], v[66:67], v[72:73]
	v_pk_mul_f32 v[74:75], v[68:69], v[74:75]
	v_pk_fma_f32 v[72:73], v[66:67], v[72:73], v[66:67]
	v_pk_fma_f32 v[74:75], v[68:69], v[74:75], v[68:69]
	v_pk_mul_f32 v[72:73], v[72:73], s[100:101] op_sel:[0,1] op_sel_hi:[1,1]
	v_pk_mul_f32 v[74:75], v[74:75], s[100:101] op_sel:[0,1] op_sel_hi:[1,1]
	v_pk_mul_f32 v[72:73], v[72:73], v[0:1] op_sel_hi:[1,0]
	v_pk_mul_f32 v[74:75], v[74:75], v[0:1] op_sel_hi:[1,0]
	v_exp_f32_e32 v72, v72
	v_exp_f32_e32 v73, v73
	v_exp_f32_e32 v74, v74
	v_exp_f32_e32 v75, v75
	v_pk_add_f32 v[72:73], v[72:73], 1.0 op_sel_hi:[1,0]
	v_pk_add_f32 v[74:75], v[74:75], 1.0 op_sel_hi:[1,0]
	v_rcp_f32_e32 v72, v72
	v_rcp_f32_e32 v73, v73
	v_rcp_f32_e32 v74, v74
	v_rcp_f32_e32 v75, v75
	v_pk_mul_f32 v[66:67], v[66:67], v[72:73]
	v_pk_mul_f32 v[68:69], v[68:69], v[74:75]
	v_pk_mul_f32 v[72:73], v[62:63], s[100:101] op_sel_hi:[1,0]
	v_pk_mul_f32 v[74:75], v[64:65], s[100:101] op_sel_hi:[1,0]
	v_pk_mul_f32 v[72:73], v[62:63], v[72:73]
	v_pk_mul_f32 v[74:75], v[64:65], v[74:75]
	v_pk_fma_f32 v[72:73], v[62:63], v[72:73], v[62:63]
	v_pk_fma_f32 v[74:75], v[64:65], v[74:75], v[64:65]
	v_pk_mul_f32 v[72:73], v[72:73], s[100:101] op_sel:[0,1] op_sel_hi:[1,1]
	v_pk_mul_f32 v[74:75], v[74:75], s[100:101] op_sel:[0,1] op_sel_hi:[1,1]
	v_pk_mul_f32 v[72:73], v[72:73], v[0:1] op_sel_hi:[1,0]
	v_pk_mul_f32 v[74:75], v[74:75], v[0:1] op_sel_hi:[1,0]
	v_exp_f32_e32 v72, v72
	v_exp_f32_e32 v73, v73
	v_exp_f32_e32 v74, v74
	v_exp_f32_e32 v75, v75
	v_pk_add_f32 v[72:73], v[72:73], 1.0 op_sel_hi:[1,0]
	v_pk_add_f32 v[74:75], v[74:75], 1.0 op_sel_hi:[1,0]
	v_rcp_f32_e32 v72, v72
	v_rcp_f32_e32 v73, v73
	v_rcp_f32_e32 v74, v74
	v_rcp_f32_e32 v75, v75
	v_pk_mul_f32 v[62:63], v[62:63], v[72:73]
	v_pk_mul_f32 v[64:65], v[64:65], v[74:75]
	v_cvt_pk_bf16_f32 v65, v64, v65
	v_cvt_pk_bf16_f32 v64, v62, v63
	v_cvt_pk_bf16_f32 v62, v66, v67
	v_cvt_pk_bf16_f32 v63, v68, v69
	v_ashrrev_i32_e32 v103, 31, v102
	s_waitcnt vmcnt(3)
	v_lshlrev_b64 v[70:71], 9, v[102:103]
	s_waitcnt vmcnt(1)
	v_mov_b64_e32 v[78:79], v[94:95]
	s_waitcnt vmcnt(0)
	v_mov_b64_e32 v[82:83], v[98:99]
	v_mov_b64_e32 v[80:81], v[96:97]
	v_mov_b64_e32 v[84:85], v[100:101]
	v_lshl_add_u64 v[66:67], v[198:199], 0, v[70:71]
	global_store_dwordx4 v[66:67], v[62:65], off
	v_pk_mul_f32 v[72:73], v[58:59], s[100:101] op_sel_hi:[1,0]
	v_pk_mul_f32 v[74:75], v[60:61], s[100:101] op_sel_hi:[1,0]
	v_pk_mul_f32 v[72:73], v[58:59], v[72:73]
	v_pk_mul_f32 v[74:75], v[60:61], v[74:75]
	v_pk_fma_f32 v[72:73], v[58:59], v[72:73], v[58:59]
	v_pk_fma_f32 v[74:75], v[60:61], v[74:75], v[60:61]
	v_pk_mul_f32 v[72:73], v[72:73], s[100:101] op_sel:[0,1] op_sel_hi:[1,1]
	v_pk_mul_f32 v[74:75], v[74:75], s[100:101] op_sel:[0,1] op_sel_hi:[1,1]
	v_pk_mul_f32 v[72:73], v[72:73], v[0:1] op_sel_hi:[1,0]
	v_pk_mul_f32 v[74:75], v[74:75], v[0:1] op_sel_hi:[1,0]
	v_exp_f32_e32 v72, v72
	v_exp_f32_e32 v73, v73
	v_exp_f32_e32 v74, v74
	v_exp_f32_e32 v75, v75
	v_pk_add_f32 v[72:73], v[72:73], 1.0 op_sel_hi:[1,0]
	v_pk_add_f32 v[74:75], v[74:75], 1.0 op_sel_hi:[1,0]
	v_rcp_f32_e32 v72, v72
	v_rcp_f32_e32 v73, v73
	v_rcp_f32_e32 v74, v74
	v_rcp_f32_e32 v75, v75
	v_pk_mul_f32 v[58:59], v[58:59], v[72:73]
	v_pk_mul_f32 v[60:61], v[60:61], v[74:75]
	v_pk_mul_f32 v[72:73], v[54:55], s[100:101] op_sel_hi:[1,0]
	v_pk_mul_f32 v[74:75], v[56:57], s[100:101] op_sel_hi:[1,0]
	v_pk_mul_f32 v[72:73], v[54:55], v[72:73]
	v_pk_mul_f32 v[74:75], v[56:57], v[74:75]
	v_pk_fma_f32 v[72:73], v[54:55], v[72:73], v[54:55]
	v_pk_fma_f32 v[74:75], v[56:57], v[74:75], v[56:57]
	v_pk_mul_f32 v[72:73], v[72:73], s[100:101] op_sel:[0,1] op_sel_hi:[1,1]
	v_pk_mul_f32 v[74:75], v[74:75], s[100:101] op_sel:[0,1] op_sel_hi:[1,1]
	v_pk_mul_f32 v[72:73], v[72:73], v[0:1] op_sel_hi:[1,0]
	v_pk_mul_f32 v[74:75], v[74:75], v[0:1] op_sel_hi:[1,0]
	v_exp_f32_e32 v72, v72
	v_exp_f32_e32 v73, v73
	v_exp_f32_e32 v74, v74
	v_exp_f32_e32 v75, v75
	v_pk_add_f32 v[72:73], v[72:73], 1.0 op_sel_hi:[1,0]
	v_pk_add_f32 v[74:75], v[74:75], 1.0 op_sel_hi:[1,0]
	v_rcp_f32_e32 v72, v72
	v_rcp_f32_e32 v73, v73
	v_rcp_f32_e32 v74, v74
	v_rcp_f32_e32 v75, v75
	v_pk_mul_f32 v[54:55], v[54:55], v[72:73]
	v_pk_mul_f32 v[56:57], v[56:57], v[74:75]
	v_cvt_pk_bf16_f32 v57, v56, v57
	v_cvt_pk_bf16_f32 v56, v54, v55
	v_cvt_pk_bf16_f32 v54, v58, v59
	v_cvt_pk_bf16_f32 v55, v60, v61
	v_mov_b64_e32 v[70:71], v[86:87]
	v_mov_b64_e32 v[74:75], v[90:91]
	v_mov_b64_e32 v[72:73], v[88:89]
	v_mov_b64_e32 v[76:77], v[92:93]
	global_store_dwordx4 v[66:67], v[54:57], off offset:64

.LBB0_543:
	s_andn2_b64 vcc, exec, s[0:1]
	s_cbranch_vccnz .LBB0_545
	s_mov_b32 s100, 0x3d372713
	s_mov_b32 s101, 0x3f4c422a
	v_mov_b32_e32 v0, 0xc038aa3b
	v_pk_mul_f32 v[56:57], v[50:51], s[100:101] op_sel_hi:[1,0]
	v_pk_mul_f32 v[58:59], v[52:53], s[100:101] op_sel_hi:[1,0]
	v_pk_mul_f32 v[56:57], v[50:51], v[56:57]
	v_pk_mul_f32 v[58:59], v[52:53], v[58:59]
	v_pk_fma_f32 v[56:57], v[50:51], v[56:57], v[50:51]
	v_pk_fma_f32 v[58:59], v[52:53], v[58:59], v[52:53]
	v_pk_mul_f32 v[56:57], v[56:57], s[100:101] op_sel:[0,1] op_sel_hi:[1,1]
	v_pk_mul_f32 v[58:59], v[58:59], s[100:101] op_sel:[0,1] op_sel_hi:[1,1]
	v_pk_mul_f32 v[56:57], v[56:57], v[0:1] op_sel_hi:[1,0]
	v_pk_mul_f32 v[58:59], v[58:59], v[0:1] op_sel_hi:[1,0]
	v_exp_f32_e32 v56, v56
	v_exp_f32_e32 v57, v57
	v_exp_f32_e32 v58, v58
	v_exp_f32_e32 v59, v59
	v_pk_add_f32 v[56:57], v[56:57], 1.0 op_sel_hi:[1,0]
	v_pk_add_f32 v[58:59], v[58:59], 1.0 op_sel_hi:[1,0]
	v_rcp_f32_e32 v56, v56
	v_rcp_f32_e32 v57, v57
	v_rcp_f32_e32 v58, v58
	v_rcp_f32_e32 v59, v59
	v_pk_mul_f32 v[50:51], v[50:51], v[56:57]
	v_pk_mul_f32 v[52:53], v[52:53], v[58:59]
	v_pk_mul_f32 v[56:57], v[46:47], s[100:101] op_sel_hi:[1,0]
	v_pk_mul_f32 v[58:59], v[48:49], s[100:101] op_sel_hi:[1,0]
	v_pk_mul_f32 v[56:57], v[46:47], v[56:57]
	v_pk_mul_f32 v[58:59], v[48:49], v[58:59]
	v_pk_fma_f32 v[56:57], v[46:47], v[56:57], v[46:47]
	v_pk_fma_f32 v[58:59], v[48:49], v[58:59], v[48:49]
	v_pk_mul_f32 v[56:57], v[56:57], s[100:101] op_sel:[0,1] op_sel_hi:[1,1]
	v_pk_mul_f32 v[58:59], v[58:59], s[100:101] op_sel:[0,1] op_sel_hi:[1,1]
	v_pk_mul_f32 v[56:57], v[56:57], v[0:1] op_sel_hi:[1,0]
	v_pk_mul_f32 v[58:59], v[58:59], v[0:1] op_sel_hi:[1,0]
	v_exp_f32_e32 v56, v56
	v_exp_f32_e32 v57, v57
	v_exp_f32_e32 v58, v58
	v_exp_f32_e32 v59, v59
	v_pk_add_f32 v[56:57], v[56:57], 1.0 op_sel_hi:[1,0]
	v_pk_add_f32 v[58:59], v[58:59], 1.0 op_sel_hi:[1,0]
	v_rcp_f32_e32 v56, v56
	v_rcp_f32_e32 v57, v57
	v_rcp_f32_e32 v58, v58
	v_rcp_f32_e32 v59, v59
	v_pk_mul_f32 v[46:47], v[46:47], v[56:57]
	v_pk_mul_f32 v[48:49], v[48:49], v[58:59]
	v_cvt_pk_bf16_f32 v49, v48, v49
	v_cvt_pk_bf16_f32 v48, v46, v47
	v_cvt_pk_bf16_f32 v46, v50, v51
	v_cvt_pk_bf16_f32 v47, v52, v53
	v_ashrrev_i32_e32 v87, 31, v86
	s_waitcnt vmcnt(3)
	v_lshlrev_b64 v[54:55], 9, v[86:87]
	s_waitcnt vmcnt(1)
	v_mov_b64_e32 v[62:63], v[78:79]
	s_waitcnt vmcnt(0)
	v_mov_b64_e32 v[66:67], v[82:83]
	v_mov_b64_e32 v[64:65], v[80:81]
	v_mov_b64_e32 v[68:69], v[84:85]
	v_lshl_add_u64 v[50:51], v[198:199], 0, v[54:55]
	global_store_dwordx4 v[50:51], v[46:49], off
	v_pk_mul_f32 v[56:57], v[42:43], s[100:101] op_sel_hi:[1,0]
	v_pk_mul_f32 v[58:59], v[44:45], s[100:101] op_sel_hi:[1,0]
	v_pk_mul_f32 v[56:57], v[42:43], v[56:57]
	v_pk_mul_f32 v[58:59], v[44:45], v[58:59]
	v_pk_fma_f32 v[56:57], v[42:43], v[56:57], v[42:43]
	v_pk_fma_f32 v[58:59], v[44:45], v[58:59], v[44:45]
	v_pk_mul_f32 v[56:57], v[56:57], s[100:101] op_sel:[0,1] op_sel_hi:[1,1]
	v_pk_mul_f32 v[58:59], v[58:59], s[100:101] op_sel:[0,1] op_sel_hi:[1,1]
	v_pk_mul_f32 v[56:57], v[56:57], v[0:1] op_sel_hi:[1,0]
	v_pk_mul_f32 v[58:59], v[58:59], v[0:1] op_sel_hi:[1,0]
	v_exp_f32_e32 v56, v56
	v_exp_f32_e32 v57, v57
	v_exp_f32_e32 v58, v58
	v_exp_f32_e32 v59, v59
	v_pk_add_f32 v[56:57], v[56:57], 1.0 op_sel_hi:[1,0]
	v_pk_add_f32 v[58:59], v[58:59], 1.0 op_sel_hi:[1,0]
	v_rcp_f32_e32 v56, v56
	v_rcp_f32_e32 v57, v57
	v_rcp_f32_e32 v58, v58
	v_rcp_f32_e32 v59, v59
	v_pk_mul_f32 v[42:43], v[42:43], v[56:57]
	v_pk_mul_f32 v[44:45], v[44:45], v[58:59]
	v_pk_mul_f32 v[56:57], v[30:31], s[100:101] op_sel_hi:[1,0]
	v_pk_mul_f32 v[58:59], v[32:33], s[100:101] op_sel_hi:[1,0]
	v_pk_mul_f32 v[56:57], v[30:31], v[56:57]
	v_pk_mul_f32 v[58:59], v[32:33], v[58:59]
	v_pk_fma_f32 v[56:57], v[30:31], v[56:57], v[30:31]
	v_pk_fma_f32 v[58:59], v[32:33], v[58:59], v[32:33]
	v_pk_mul_f32 v[56:57], v[56:57], s[100:101] op_sel:[0,1] op_sel_hi:[1,1]
	v_pk_mul_f32 v[58:59], v[58:59], s[100:101] op_sel:[0,1] op_sel_hi:[1,1]
	v_pk_mul_f32 v[56:57], v[56:57], v[0:1] op_sel_hi:[1,0]
	v_pk_mul_f32 v[58:59], v[58:59], v[0:1] op_sel_hi:[1,0]
	v_exp_f32_e32 v56, v56
	v_exp_f32_e32 v57, v57
	v_exp_f32_e32 v58, v58
	v_exp_f32_e32 v59, v59
	v_pk_add_f32 v[56:57], v[56:57], 1.0 op_sel_hi:[1,0]
	v_pk_add_f32 v[58:59], v[58:59], 1.0 op_sel_hi:[1,0]
	v_rcp_f32_e32 v56, v56
	v_rcp_f32_e32 v57, v57
	v_rcp_f32_e32 v58, v58
	v_rcp_f32_e32 v59, v59
	v_pk_mul_f32 v[30:31], v[30:31], v[56:57]
	v_pk_mul_f32 v[32:33], v[32:33], v[58:59]
	v_cvt_pk_bf16_f32 v33, v32, v33
	v_cvt_pk_bf16_f32 v32, v30, v31
	v_cvt_pk_bf16_f32 v30, v42, v43
	v_cvt_pk_bf16_f32 v31, v44, v45
	v_mov_b64_e32 v[54:55], v[70:71]
	v_mov_b64_e32 v[58:59], v[74:75]
	v_mov_b64_e32 v[56:57], v[72:73]
	v_mov_b64_e32 v[60:61], v[76:77]
	global_store_dwordx4 v[50:51], v[30:33], off offset:64

.LBB0_549:
	s_mov_b32 s100, 0x3d372713
	s_mov_b32 s101, 0x3f4c422a
	v_mov_b32_e32 v0, 0xc038aa3b
	v_pk_mul_f32 v[24:25], v[18:19], s[100:101] op_sel_hi:[1,0]
	v_pk_mul_f32 v[26:27], v[20:21], s[100:101] op_sel_hi:[1,0]
	v_pk_mul_f32 v[24:25], v[18:19], v[24:25]
	v_pk_mul_f32 v[26:27], v[20:21], v[26:27]
	v_pk_fma_f32 v[24:25], v[18:19], v[24:25], v[18:19]
	v_pk_fma_f32 v[26:27], v[20:21], v[26:27], v[20:21]
	v_pk_mul_f32 v[24:25], v[24:25], s[100:101] op_sel:[0,1] op_sel_hi:[1,1]
	v_pk_mul_f32 v[26:27], v[26:27], s[100:101] op_sel:[0,1] op_sel_hi:[1,1]
	v_pk_mul_f32 v[24:25], v[24:25], v[0:1] op_sel_hi:[1,0]
	v_pk_mul_f32 v[26:27], v[26:27], v[0:1] op_sel_hi:[1,0]
	v_exp_f32_e32 v24, v24
	v_exp_f32_e32 v25, v25
	v_exp_f32_e32 v26, v26
	v_exp_f32_e32 v27, v27
	v_pk_add_f32 v[24:25], v[24:25], 1.0 op_sel_hi:[1,0]
	v_pk_add_f32 v[26:27], v[26:27], 1.0 op_sel_hi:[1,0]
	v_rcp_f32_e32 v24, v24
	v_rcp_f32_e32 v25, v25
	v_rcp_f32_e32 v26, v26
	v_rcp_f32_e32 v27, v27
	v_pk_mul_f32 v[18:19], v[18:19], v[24:25]
	v_pk_mul_f32 v[20:21], v[20:21], v[26:27]
	v_pk_mul_f32 v[24:25], v[14:15], s[100:101] op_sel_hi:[1,0]
	v_pk_mul_f32 v[26:27], v[16:17], s[100:101] op_sel_hi:[1,0]
	v_pk_mul_f32 v[24:25], v[14:15], v[24:25]
	v_pk_mul_f32 v[26:27], v[16:17], v[26:27]
	v_pk_fma_f32 v[24:25], v[14:15], v[24:25], v[14:15]
	v_pk_fma_f32 v[26:27], v[16:17], v[26:27], v[16:17]
	v_pk_mul_f32 v[24:25], v[24:25], s[100:101] op_sel:[0,1] op_sel_hi:[1,1]
	v_pk_mul_f32 v[26:27], v[26:27], s[100:101] op_sel:[0,1] op_sel_hi:[1,1]
	v_pk_mul_f32 v[24:25], v[24:25], v[0:1] op_sel_hi:[1,0]
	v_pk_mul_f32 v[26:27], v[26:27], v[0:1] op_sel_hi:[1,0]
	v_exp_f32_e32 v24, v24
	v_exp_f32_e32 v25, v25
	v_exp_f32_e32 v26, v26
	v_exp_f32_e32 v27, v27
	v_pk_add_f32 v[24:25], v[24:25], 1.0 op_sel_hi:[1,0]
	v_pk_add_f32 v[26:27], v[26:27], 1.0 op_sel_hi:[1,0]
	v_rcp_f32_e32 v24, v24
	v_rcp_f32_e32 v25, v25
	v_rcp_f32_e32 v26, v26
	v_rcp_f32_e32 v27, v27
	v_pk_mul_f32 v[14:15], v[14:15], v[24:25]
	v_pk_mul_f32 v[16:17], v[16:17], v[26:27]
	v_cvt_pk_bf16_f32 v17, v16, v17
	v_cvt_pk_bf16_f32 v16, v14, v15
	v_cvt_pk_bf16_f32 v14, v18, v19
	v_cvt_pk_bf16_f32 v15, v20, v21
	v_ashrrev_i32_e32 v31, 31, v30
	v_lshlrev_b64 v[22:23], 9, v[30:31]
	v_lshl_add_u64 v[18:19], v[198:199], 0, v[22:23]
	global_store_dwordx4 v[18:19], v[14:17], off
	v_pk_mul_f32 v[24:25], v[10:11], s[100:101] op_sel_hi:[1,0]
	v_pk_mul_f32 v[26:27], v[12:13], s[100:101] op_sel_hi:[1,0]
	v_pk_mul_f32 v[24:25], v[10:11], v[24:25]
	v_pk_mul_f32 v[26:27], v[12:13], v[26:27]
	v_pk_fma_f32 v[24:25], v[10:11], v[24:25], v[10:11]
	v_pk_fma_f32 v[26:27], v[12:13], v[26:27], v[12:13]
	v_pk_mul_f32 v[24:25], v[24:25], s[100:101] op_sel:[0,1] op_sel_hi:[1,1]
	v_pk_mul_f32 v[26:27], v[26:27], s[100:101] op_sel:[0,1] op_sel_hi:[1,1]
	v_pk_mul_f32 v[24:25], v[24:25], v[0:1] op_sel_hi:[1,0]
	v_pk_mul_f32 v[26:27], v[26:27], v[0:1] op_sel_hi:[1,0]
	v_exp_f32_e32 v24, v24
	v_exp_f32_e32 v25, v25
	v_exp_f32_e32 v26, v26
	v_exp_f32_e32 v27, v27
	v_pk_add_f32 v[24:25], v[24:25], 1.0 op_sel_hi:[1,0]
	v_pk_add_f32 v[26:27], v[26:27], 1.0 op_sel_hi:[1,0]
	v_rcp_f32_e32 v24, v24
	v_rcp_f32_e32 v25, v25
	v_rcp_f32_e32 v26, v26
	v_rcp_f32_e32 v27, v27
	v_pk_mul_f32 v[10:11], v[10:11], v[24:25]
	v_pk_mul_f32 v[12:13], v[12:13], v[26:27]
	v_pk_mul_f32 v[24:25], v[6:7], s[100:101] op_sel_hi:[1,0]
	v_pk_mul_f32 v[26:27], v[8:9], s[100:101] op_sel_hi:[1,0]
	v_pk_mul_f32 v[24:25], v[6:7], v[24:25]
	v_pk_mul_f32 v[26:27], v[8:9], v[26:27]
	v_pk_fma_f32 v[24:25], v[6:7], v[24:25], v[6:7]
	v_pk_fma_f32 v[26:27], v[8:9], v[26:27], v[8:9]
	v_pk_mul_f32 v[24:25], v[24:25], s[100:101] op_sel:[0,1] op_sel_hi:[1,1]
	v_pk_mul_f32 v[26:27], v[26:27], s[100:101] op_sel:[0,1] op_sel_hi:[1,1]
	v_pk_mul_f32 v[24:25], v[24:25], v[0:1] op_sel_hi:[1,0]
	v_pk_mul_f32 v[26:27], v[26:27], v[0:1] op_sel_hi:[1,0]
	v_exp_f32_e32 v24, v24
	v_exp_f32_e32 v25, v25
	v_exp_f32_e32 v26, v26
	v_exp_f32_e32 v27, v27
	v_pk_add_f32 v[24:25], v[24:25], 1.0 op_sel_hi:[1,0]
	v_pk_add_f32 v[26:27], v[26:27], 1.0 op_sel_hi:[1,0]
	v_rcp_f32_e32 v24, v24
	v_rcp_f32_e32 v25, v25
	v_rcp_f32_e32 v26, v26
	v_rcp_f32_e32 v27, v27
	v_pk_mul_f32 v[6:7], v[6:7], v[24:25]
	v_pk_mul_f32 v[8:9], v[8:9], v[26:27]
	v_cvt_pk_bf16_f32 v9, v8, v9
	v_cvt_pk_bf16_f32 v8, v6, v7
	v_cvt_pk_bf16_f32 v6, v10, v11
	v_cvt_pk_bf16_f32 v7, v12, v13
	global_store_dwordx4 v[18:19], v[6:9], off offset:64
